# P3 prologue: last PROJ panel counter prefetched with the first poll
# baseline (speedup 1.0000x reference)
; __device__ __forceinline__ unsigned xb_ld(unsigned* p)              { return __hip_atomic_load(p, __ATOMIC_RELAXED, __HIP_MEMORY_SCOPE_AGENT); }
; #define XB_SPIN(cond, bar) do { unsigned _sp = 0; while (cond) { __builtin_amdgcn_s_sleep(1); \
;     if ((++_sp & 255u) == 0u) { if (xb_ld(&(bar)[XB_TMO])) break; if (_sp > XB_SPIN_CAP) { atomicAdd(&(bar)[XB_TMO], 1u); break; } } } } while (0)
; __global__ void __launch_bounds__(NTHR, 2) k_main(Args a) {
;     ...
;         if (tid == 0) {
;             int plo = 0, phi = T / 256 - 1;
;             if (nb == 256) { const int r0 = min(max(64 * bid - 128, 0), max(128 * (bid >> 1) - 3, 0)), r1 = max(64 * bid + 63, 128 * (bid >> 1) + 127); plo = r0 >> 8; phi = r1 >> 8; }
;             for (int p = plo; p <= phi; ++p) { unsigned* cw = &((unsigned*)ws)[8192 + 16 * p]; XB_SPIN(xb_ld(cw) < (unsigned)(PS / 256), (unsigned*)ws); }
;             __builtin_amdgcn_fence(__ATOMIC_ACQUIRE, "agent");
;             asm volatile("s_waitcnt vmcnt(0)" ::: "memory");
.LBB0_150:
	s_cmp_gt_i32 s3, s14
	s_cbranch_scc1 .LBB0_166
	s_mov_b32 s5, 0
	v_mov_b32_e32 v1, 0x8000
	v_mov_b32_e32 v2, 0
	s_lshl_b32 s4, s14, 6
	s_add_u32 s6, s90, s4
	s_addc_u32 s7, s91, 0
	global_load_dword v210, v1, s[6:7] sc1
	s_branch .LBB0_154

; __device__ __forceinline__ unsigned xb_ld(unsigned* p)              { return __hip_atomic_load(p, __ATOMIC_RELAXED, __HIP_MEMORY_SCOPE_AGENT); }
; #define XB_SPIN(cond, bar) do { unsigned _sp = 0; while (cond) { __builtin_amdgcn_s_sleep(1); \
;     if ((++_sp & 255u) == 0u) { if (xb_ld(&(bar)[XB_TMO])) break; if (_sp > XB_SPIN_CAP) { atomicAdd(&(bar)[XB_TMO], 1u); break; } } } } while (0)
; __global__ void __launch_bounds__(NTHR, 2) k_main(Args a) {
;     ...
;             for (int p = plo; p <= phi; ++p) { unsigned* cw = &((unsigned*)ws)[8192 + 16 * p]; XB_SPIN(xb_ld(cw) < (unsigned)(PS / 256), (unsigned*)ws); }
.LBB0_154:
	s_cmp_lg_u32 s3, s14
	s_cbranch_scc1 .Lp3_poll
	s_waitcnt vmcnt(0)
	v_cmp_lt_u32_e32 vcc, 8, v210
	s_cbranch_vccnz .LBB0_166
